# stick-breaking attention: p1 QK chain first, then the p0 chain on a 4-deep fragment ring with the p1 half's weight computation (step A) issued in the gaps of the p0 MFMAs
# speedup vs baseline: 1.0045x; 1.0045x over previous
.LBB0_41:
	s_add_i32 s0, s42, -1
	v_cmp_le_i32_e32 vcc, s2, v198
	s_and_b32 s45, s0, 1
	s_cbranch_vccnz .LBB0_44
	v_cmp_gt_f32_e32 vcc, s58, v172
	s_cmp_eq_u64 vcc, exec
	s_cbranch_scc1 .LBB0_44
	s_mul_i32 s0, s45, 0x8c00
	s_add_i32 s0, s0, 0
	v_add_u32_e32 v0, s0, v189
	v_add_u32_e32 v173, v0, v188
	ds_read_b128 v[174:177], v173 offset:8704
	ds_read_b128 v[200:203], v173 offset:8736
	ds_read_b128 v[204:207], v173 offset:8768
	ds_read_b128 v[208:211], v173 offset:8800
	ds_read_b128 v[212:215], v173 offset:8832
	ds_read_b128 v[216:219], v173 offset:8864
	ds_read_b128 v[220:223], v173 offset:8896
	ds_read_b128 v[224:227], v173 offset:8928
	ds_read_b128 v[66:69], v173
	ds_read_b128 v[232:235], v173 offset:32
	s_setprio 1
	s_waitcnt lgkmcnt(9)
	v_mfma_f32_32x32x16_bf16 v[82:97], v[174:177], v[98:101], 0
	s_waitcnt lgkmcnt(8)
	v_mfma_f32_32x32x16_bf16 v[82:97], v[200:203], v[102:105], v[82:97]
	s_waitcnt lgkmcnt(7)
	v_mfma_f32_32x32x16_bf16 v[82:97], v[204:207], v[106:109], v[82:97]
	s_waitcnt lgkmcnt(6)
	v_mfma_f32_32x32x16_bf16 v[82:97], v[208:211], v[110:113], v[82:97]
	s_waitcnt lgkmcnt(5)
	v_mfma_f32_32x32x16_bf16 v[82:97], v[212:215], v[114:117], v[82:97]
	s_waitcnt lgkmcnt(4)
	v_mfma_f32_32x32x16_bf16 v[82:97], v[216:219], v[118:121], v[82:97]
	ds_read_b128 v[216:219], v173 offset:64
	s_waitcnt lgkmcnt(4)
	v_mfma_f32_32x32x16_bf16 v[82:97], v[220:223], v[122:125], v[82:97]
	ds_read_b128 v[220:223], v173 offset:96
	s_waitcnt lgkmcnt(4)
	v_mfma_f32_32x32x16_bf16 v[82:97], v[224:227], v[126:129], v[82:97]
	ds_read_b128 v[224:227], v173 offset:128
	s_waitcnt lgkmcnt(4)
	v_mfma_f32_32x32x16_bf16 v[66:81], v[66:69], v[98:101], 0
	s_waitcnt lgkmcnt(3)
	v_mfma_f32_32x32x16_bf16 v[66:81], v[232:235], v[102:105], v[66:81]
	ds_read_b128 v[232:235], v173 offset:160
	s_nop 3
	v_mov_b32_e32 v236, 1.0
	v_cmp_gt_i32_e32 vcc, 28, v159
	s_cmp_eq_u64 vcc, 0
	s_cbranch_scc1 .Lstk_nm1
	v_cmp_lt_i32_e64 s[0:1], 0, v159
	v_cmp_lt_i32_e64 s[8:9], 1, v159
	v_cmp_lt_i32_e64 s[10:11], 2, v159
	v_cmp_lt_i32_e64 s[12:13], 3, v159
	v_cndmask_b32_e64 v82, v231, v82, s[0:1]
	v_cndmask_b32_e64 v83, v231, v83, s[8:9]
	v_cndmask_b32_e64 v84, v231, v84, s[10:11]
	v_cndmask_b32_e64 v85, v231, v85, s[12:13]
	v_cmp_lt_i32_e64 s[0:1], 8, v159
	v_cmp_lt_i32_e64 s[8:9], 9, v159
	v_cmp_lt_i32_e64 s[10:11], 10, v159
	v_cmp_lt_i32_e64 s[12:13], 11, v159
	v_cndmask_b32_e64 v86, v231, v86, s[0:1]
	v_cndmask_b32_e64 v87, v231, v87, s[8:9]
	v_cndmask_b32_e64 v88, v231, v88, s[10:11]
	v_cndmask_b32_e64 v89, v231, v89, s[12:13]
	v_cmp_lt_i32_e64 s[0:1], 16, v159
	v_cmp_lt_i32_e64 s[8:9], 17, v159
	v_cmp_lt_i32_e64 s[10:11], 18, v159
	v_cmp_lt_i32_e64 s[12:13], 19, v159
	v_cndmask_b32_e64 v90, v231, v90, s[0:1]
	v_cndmask_b32_e64 v91, v231, v91, s[8:9]
	v_cndmask_b32_e64 v92, v231, v92, s[10:11]
	v_cndmask_b32_e64 v93, v231, v93, s[12:13]
	v_cmp_lt_i32_e64 s[0:1], 24, v159
	v_cmp_lt_i32_e64 s[8:9], 25, v159
	v_cmp_lt_i32_e64 s[10:11], 26, v159
	v_cmp_lt_i32_e64 s[12:13], 27, v159
	v_cndmask_b32_e64 v94, v231, v94, s[0:1]
	v_cndmask_b32_e64 v95, v231, v95, s[8:9]
	v_cndmask_b32_e64 v96, v231, v96, s[10:11]
	v_cndmask_b32_e64 v97, v231, v97, s[12:13]
.Lstk_nm1:
	s_waitcnt lgkmcnt(3)
	v_mfma_f32_32x32x16_bf16 v[66:81], v[216:219], v[106:109], v[66:81]
	ds_read_b128 v[216:219], v173 offset:192
	v_exp_f32_e64 v200, -|v82|
	v_exp_f32_e64 v201, -|v83|
	v_exp_f32_e64 v202, -|v84|
	v_exp_f32_e64 v203, -|v85|
	v_pk_add_f32 v[200:201], v[200:201], v[236:237] op_sel_hi:[1,0]
	v_max_i32_e32 v174, 0, v82
	v_max_i32_e32 v175, 0, v83
	v_log_f32_e32 v200, v200
	v_log_f32_e32 v201, v201
	v_exp_f32_e64 v204, -|v86|
	v_exp_f32_e64 v205, -|v87|
	v_pk_add_f32 v[202:203], v[202:203], v[236:237] op_sel_hi:[1,0]
	s_waitcnt lgkmcnt(3)
	v_mfma_f32_32x32x16_bf16 v[66:81], v[220:223], v[110:113], v[66:81]
	ds_read_b128 v[220:223], v173 offset:224
	v_max_i32_e32 v176, 0, v84
	v_max_i32_e32 v177, 0, v85
	v_log_f32_e32 v202, v202
	v_log_f32_e32 v203, v203
	v_pk_add_f32 v[200:201], v[200:201], v[174:175]
	v_pk_add_f32 v[82:83], v[82:83], v[200:201] neg_lo:[0,1] neg_hi:[0,1]
	v_exp_f32_e64 v206, -|v88|
	v_exp_f32_e64 v207, -|v89|
	v_pk_add_f32 v[204:205], v[204:205], v[236:237] op_sel_hi:[1,0]
	v_max_i32_e32 v174, 0, v86
	v_max_i32_e32 v175, 0, v87
	v_log_f32_e32 v204, v204
	s_waitcnt lgkmcnt(3)
	v_mfma_f32_32x32x16_bf16 v[66:81], v[224:227], v[114:117], v[66:81]
	v_log_f32_e32 v205, v205
	v_pk_add_f32 v[202:203], v[202:203], v[176:177]
	v_pk_add_f32 v[84:85], v[84:85], v[202:203] neg_lo:[0,1] neg_hi:[0,1]
	v_exp_f32_e64 v208, -|v90|
	v_exp_f32_e64 v209, -|v91|
	v_pk_add_f32 v[206:207], v[206:207], v[236:237] op_sel_hi:[1,0]
	v_max_i32_e32 v176, 0, v88
	v_max_i32_e32 v177, 0, v89
	v_log_f32_e32 v206, v206
	v_log_f32_e32 v207, v207
	v_pk_add_f32 v[204:205], v[204:205], v[174:175]
	v_pk_add_f32 v[86:87], v[86:87], v[204:205] neg_lo:[0,1] neg_hi:[0,1]
	s_waitcnt lgkmcnt(2)
	v_mfma_f32_32x32x16_bf16 v[66:81], v[232:235], v[118:121], v[66:81]
	v_exp_f32_e64 v210, -|v92|
	v_exp_f32_e64 v211, -|v93|
	v_pk_add_f32 v[208:209], v[208:209], v[236:237] op_sel_hi:[1,0]
	v_max_i32_e32 v174, 0, v90
	v_max_i32_e32 v175, 0, v91
	v_log_f32_e32 v208, v208
	v_log_f32_e32 v209, v209
	v_pk_add_f32 v[206:207], v[206:207], v[176:177]
	v_pk_add_f32 v[88:89], v[88:89], v[206:207] neg_lo:[0,1] neg_hi:[0,1]
	v_exp_f32_e64 v212, -|v94|
	v_exp_f32_e64 v213, -|v95|
	v_pk_add_f32 v[210:211], v[210:211], v[236:237] op_sel_hi:[1,0]
	s_waitcnt lgkmcnt(1)
	v_mfma_f32_32x32x16_bf16 v[66:81], v[216:219], v[122:125], v[66:81]
	v_max_i32_e32 v176, 0, v92
	v_max_i32_e32 v177, 0, v93
	v_log_f32_e32 v210, v210
	v_log_f32_e32 v211, v211
	v_pk_add_f32 v[208:209], v[208:209], v[174:175]
	v_pk_add_f32 v[90:91], v[90:91], v[208:209] neg_lo:[0,1] neg_hi:[0,1]
	v_exp_f32_e64 v214, -|v96|
	v_exp_f32_e64 v215, -|v97|
	v_pk_add_f32 v[212:213], v[212:213], v[236:237] op_sel_hi:[1,0]
	v_max_i32_e32 v174, 0, v94
	v_max_i32_e32 v175, 0, v95
	v_log_f32_e32 v212, v212
	s_waitcnt lgkmcnt(0)
	v_mfma_f32_32x32x16_bf16 v[66:81], v[220:223], v[126:129], v[66:81]
	v_log_f32_e32 v213, v213
	v_pk_add_f32 v[210:211], v[210:211], v[176:177]
	v_pk_add_f32 v[92:93], v[92:93], v[210:211] neg_lo:[0,1] neg_hi:[0,1]
	v_pk_add_f32 v[214:215], v[214:215], v[236:237] op_sel_hi:[1,0]
	v_max_i32_e32 v176, 0, v96
	v_max_i32_e32 v177, 0, v97
	v_log_f32_e32 v214, v214
	v_log_f32_e32 v215, v215
	v_pk_add_f32 v[212:213], v[212:213], v[174:175]
	v_pk_add_f32 v[94:95], v[94:95], v[212:213] neg_lo:[0,1] neg_hi:[0,1]
	v_pk_add_f32 v[214:215], v[214:215], v[176:177]
	v_pk_add_f32 v[96:97], v[96:97], v[214:215] neg_lo:[0,1] neg_hi:[0,1]
	s_setprio 0
	v_cndmask_b32_e64 v173, 0, 1.0, s[4:5]
	v_pk_add_f32 v[174:175], v[200:201], v[202:203]
	v_add_f32_e32 v216, v174, v175
	v_mov_b32_e32 v220, v216
	v_pk_add_f32 v[176:177], v[204:205], v[206:207]
	v_add_f32_e32 v217, v176, v177
	v_mov_b32_e32 v221, v217
	v_pk_add_f32 v[174:175], v[208:209], v[210:211]
	v_add_f32_e32 v218, v174, v175
	v_mov_b32_e32 v222, v218
	v_pk_add_f32 v[176:177], v[212:213], v[214:215]
	v_add_f32_e32 v219, v176, v177
	v_mov_b32_e32 v223, v219
	s_nop 1
	v_permlane32_swap_b32_e32 v216, v220
	v_permlane32_swap_b32_e32 v217, v221
	v_permlane32_swap_b32_e32 v218, v222
	v_permlane32_swap_b32_e32 v219, v223
	v_add_f32_e32 v216, v216, v220
	v_add_f32_e32 v217, v217, v221
	v_add_f32_e32 v218, v218, v222
	v_add_f32_e32 v219, v219, v223
	v_fma_f32 v233, -v223, v173, v172
	v_sub_f32_e32 v232, v233, v215
	v_sub_f32_e32 v229, v232, v214
	v_sub_f32_e32 v228, v229, v213
	v_pk_add_f32 v[96:97], v[96:97], v[232:233]
	v_pk_add_f32 v[94:95], v[94:95], v[228:229]
	v_exp_f32_e32 v96, v96
	v_exp_f32_e32 v97, v97
	v_exp_f32_e32 v94, v94
	v_exp_f32_e32 v95, v95
	v_sub_f32_e32 v227, v172, v219
	v_fma_f32 v177, -v222, v173, v227
	v_sub_f32_e32 v176, v177, v211
	v_sub_f32_e32 v235, v176, v210
	v_sub_f32_e32 v234, v235, v209
	v_pk_add_f32 v[92:93], v[92:93], v[176:177]
	v_pk_add_f32 v[90:91], v[90:91], v[234:235]
	v_exp_f32_e32 v92, v92
	v_exp_f32_e32 v93, v93
	v_exp_f32_e32 v90, v90
	v_exp_f32_e32 v91, v91
	v_sub_f32_e32 v226, v227, v218
	v_fma_f32 v233, -v221, v173, v226
	v_sub_f32_e32 v232, v233, v207
	v_sub_f32_e32 v229, v232, v206
	v_sub_f32_e32 v228, v229, v205
	v_pk_add_f32 v[88:89], v[88:89], v[232:233]
	v_pk_add_f32 v[86:87], v[86:87], v[228:229]
	v_exp_f32_e32 v88, v88
	v_exp_f32_e32 v89, v89
	v_exp_f32_e32 v86, v86
	v_exp_f32_e32 v87, v87
	v_sub_f32_e32 v227, v226, v217
	v_fma_f32 v177, -v220, v173, v227
	v_sub_f32_e32 v182, v227, v216
	v_sub_f32_e32 v176, v177, v203
	v_sub_f32_e32 v235, v176, v202
	v_sub_f32_e32 v234, v235, v201
	v_pk_add_f32 v[84:85], v[84:85], v[176:177]
	v_pk_add_f32 v[82:83], v[82:83], v[234:235]
	v_exp_f32_e32 v84, v84
	v_exp_f32_e32 v85, v85
	v_exp_f32_e32 v82, v82
	v_exp_f32_e32 v83, v83
	v_add_u32_e32 v199, 32, v159
	v_cmp_gt_i32_e32 vcc, 28, v199
	s_cmp_eq_u64 vcc, 0
	s_cbranch_scc1 .Lstk_nm0
	v_cmp_lt_i32_e64 s[0:1], 0, v199
	v_cmp_lt_i32_e64 s[8:9], 1, v199
	v_cmp_lt_i32_e64 s[10:11], 2, v199
	v_cmp_lt_i32_e64 s[12:13], 3, v199
	v_cndmask_b32_e64 v66, v231, v66, s[0:1]
	v_cndmask_b32_e64 v67, v231, v67, s[8:9]
	v_cndmask_b32_e64 v68, v231, v68, s[10:11]
	v_cndmask_b32_e64 v69, v231, v69, s[12:13]
	v_cmp_lt_i32_e64 s[0:1], 8, v199
	v_cmp_lt_i32_e64 s[8:9], 9, v199
	v_cmp_lt_i32_e64 s[10:11], 10, v199
	v_cmp_lt_i32_e64 s[12:13], 11, v199
	v_cndmask_b32_e64 v70, v231, v70, s[0:1]
	v_cndmask_b32_e64 v71, v231, v71, s[8:9]
	v_cndmask_b32_e64 v72, v231, v72, s[10:11]
	v_cndmask_b32_e64 v73, v231, v73, s[12:13]
	v_cmp_lt_i32_e64 s[0:1], 16, v199
	v_cmp_lt_i32_e64 s[8:9], 17, v199
	v_cmp_lt_i32_e64 s[10:11], 18, v199
	v_cmp_lt_i32_e64 s[12:13], 19, v199
	v_cndmask_b32_e64 v74, v231, v74, s[0:1]
	v_cndmask_b32_e64 v75, v231, v75, s[8:9]
	v_cndmask_b32_e64 v76, v231, v76, s[10:11]
	v_cndmask_b32_e64 v77, v231, v77, s[12:13]
	v_cmp_lt_i32_e64 s[0:1], 24, v199
	v_cmp_lt_i32_e64 s[8:9], 25, v199
	v_cmp_lt_i32_e64 s[10:11], 26, v199
	v_cmp_lt_i32_e64 s[12:13], 27, v199
	v_cndmask_b32_e64 v78, v231, v78, s[0:1]
	v_cndmask_b32_e64 v79, v231, v79, s[8:9]
	v_cndmask_b32_e64 v80, v231, v80, s[10:11]
	v_cndmask_b32_e64 v81, v231, v81, s[12:13]
